# split-phase barrier 7 for the 128 workgroups that open P7 with a sample-row piece: arrive only; wave 0 polls asynchronously inside the piece's K-loop and completes the wait before the last iteration's
# speedup vs baseline: 1.0074x; 1.0037x over previous
; __device__ __forceinline__ unsigned xb_ld(unsigned* p)              { return __hip_atomic_load(p, __ATOMIC_RELAXED, __HIP_MEMORY_SCOPE_AGENT); }
; __device__ __forceinline__ unsigned xb_add(unsigned* p, unsigned v) { return __hip_atomic_fetch_add(p, v, __ATOMIC_RELAXED, __HIP_MEMORY_SCOPE_AGENT); }
; #define XB_SPIN(cond, bar) do { unsigned _sp = 0; while (cond) { __builtin_amdgcn_s_sleep(1); \
;     if ((++_sp & 255u) == 0u) { if (xb_ld(&(bar)[XB_TMO])) break; if (_sp > XB_SPIN_CAP) { atomicAdd(&(bar)[XB_TMO], 1u); break; } } } } while (0)
; __device__ __forceinline__ void xcd_barrier(const XcdBarrier& b) {
;     ...
;         const unsigned old = xb_add(&bar[XB_XSUB(b.x)], 1u);
;         const unsigned gen = old / nloc;
;         if (old + 1u == (gen + 1u) * nloc) {
;             __builtin_amdgcn_fence(__ATOMIC_RELEASE, "agent");
;             asm volatile("s_waitcnt vmcnt(0)" ::: "memory");
;             const unsigned og = xb_add(&bar[XB_TOP], 1u);
;             const unsigned tg = og / nx;
;             if (og + 1u == (tg + 1u) * nx) xb_add(&bar[XB_TOPGEN], 1u);
;             else XB_SPIN(xb_ld(&bar[XB_TOPGEN]) == tg, bar);
;             __builtin_amdgcn_fence(__ATOMIC_ACQUIRE, "agent");
;             xb_add(&bar[XB_XGEN(b.x)], 1u);
;             asm volatile("s_waitcnt vmcnt(0)" ::: "memory");
;         } else {
;             XB_SPIN(xb_ld(&bar[XB_XGEN(b.x)]) == gen, bar);
;             __builtin_amdgcn_fence(__ATOMIC_ACQUIRE, "agent");
.LBB0_1002:
	s_or_b64 exec, exec, s[14:15]
	v_cvt_f32_u32_e32 v4, v2
	s_waitcnt vmcnt(0)
	v_readfirstlane_b32 s3, v3
	v_sub_u32_e32 v3, 0, v2
	v_rcp_iflag_f32_e32 v4, v4
	v_add_u32_e32 v5, s3, v1
	v_mul_f32_e32 v4, 0x4f7ffffe, v4
	v_cvt_u32_f32_e32 v4, v4
	v_mul_lo_u32 v1, v3, v4
	v_mul_hi_u32 v1, v4, v1
	v_add_u32_e32 v1, v4, v1
	v_mul_hi_u32 v1, v5, v1
	v_mul_lo_u32 v3, v1, v2
	v_sub_u32_e32 v3, v5, v3
	v_add_u32_e32 v4, 1, v1
	v_cmp_ge_u32_e32 vcc, v3, v2
	s_nop 1
	v_cndmask_b32_e32 v1, v1, v4, vcc
	v_sub_u32_e32 v4, v3, v2
	v_cndmask_b32_e32 v3, v3, v4, vcc
	v_add_u32_e32 v4, 1, v1
	v_cmp_ge_u32_e32 vcc, v3, v2
	v_add_u32_e32 v3, 1, v5
	s_nop 0
	v_cndmask_b32_e32 v1, v1, v4, vcc
	v_mul_lo_u32 v4, v2, v1
	v_add_u32_e32 v2, v4, v2
	v_cmp_ne_u32_e32 vcc, v3, v2
	s_and_saveexec_b64 s[12:13], vcc
	s_xor_b64 s[12:13], exec, s[12:13]
	s_cbranch_execz .LBB0_1016
	s_cmp_lg_u32 s100, 0
	s_cbranch_scc1 .Lsp7_norm
	s_cmpk_gt_u32 s2, 0x7f
	s_cbranch_scc1 .Lsp7_norm
	v_readfirstlane_b32 s101, v1
	s_mov_b32 s99, 0x7777
	s_branch .LBB0_1016
.Lsp7_norm:
	s_waitcnt lgkmcnt(0)
	buffer_inv sc1
	v_mov_b32_e32 v0, 0x2000
	global_load_dword v0, v0, s[10:11] offset:1024 sc1
	s_add_u32 s18, s10, 0x2400
	s_addc_u32 s19, s11, 0
	s_waitcnt vmcnt(0)
	v_cmp_eq_u32_e32 vcc, v0, v1
	s_and_saveexec_b64 s[14:15], vcc
	s_cbranch_execz .LBB0_1015
	s_add_u32 s16, s68, 0x80200
	s_addc_u32 s17, s69, 0
	s_mov_b32 s3, 1
	s_mov_b64 s[20:21], 0
	v_mov_b32_e32 v0, 0
	s_branch .LBB0_1006

; __device__ __forceinline__ unsigned xb_ld(unsigned* p)              { return __hip_atomic_load(p, __ATOMIC_RELAXED, __HIP_MEMORY_SCOPE_AGENT); }
; #define XB_SPIN(cond, bar) do { unsigned _sp = 0; while (cond) { __builtin_amdgcn_s_sleep(1); \
;     if ((++_sp & 255u) == 0u) { if (xb_ld(&(bar)[XB_TMO])) break; if (_sp > XB_SPIN_CAP) { atomicAdd(&(bar)[XB_TMO], 1u); break; } } } } while (0)
; __device__ __forceinline__ void xcd_barrier(const XcdBarrier& b) {
;     ...
;             XB_SPIN(xb_ld(&bar[XB_XGEN(b.x)]) == gen, bar);
;             __builtin_amdgcn_fence(__ATOMIC_ACQUIRE, "agent");
.Lsp7_h:
	s_cmp_eq_u32 s73, 4
	s_cbranch_scc0 .Lsp7_h2
	s_mov_b64 exec, 1
	s_lshl_b32 s98, s33, 8
	s_add_u32 s98, s98, 0x82400
	v_mov_b32_e32 v246, s98
	global_load_dword v247, v246, s[68:69] sc1
	s_mov_b64 exec, -1
	s_branch .Lsp7_back
.Lsp7_h2:
	s_cmp_eq_u32 s73, 6
	s_cbranch_scc0 .Lsp7_back
	s_mov_b64 exec, 1
	v_mov_b32_e32 v248, s101
	s_mov_b32 s98, 0x40000
.Lsp7_chk:
	v_cmp_ne_u32_e32 vcc, v247, v248
	s_cbranch_vccnz .Lsp7_ok
	s_sleep 1
	global_load_dword v247, v246, s[68:69] sc1
	s_waitcnt vmcnt(0)
	s_sub_u32 s98, s98, 1
	s_cmp_eq_u32 s98, 0
	s_cbranch_scc0 .Lsp7_chk
.Lsp7_ok:
	buffer_inv sc1
	s_mov_b32 s99, 0
	s_mov_b64 exec, -1
	s_branch .Lsp7_back

; #define PG8_STAGEA(bufoff, gbase, voff) do { _Pragma("unroll") for (int _i = 0; _i < 2; ++_i) \
;         __builtin_amdgcn_global_load_lds((const unsigned*)((const char*)(gbase) + (voff)[_i]), (PG8_LAS unsigned*)(lds + (bufoff) + ldsw + _i * 8192), 16, 0, AUXA); } while (0)
; #define PG8_LDA(dst, b, h) do { _Pragma("unroll") for (int m = 0; m < 4; ++m) _Pragma("unroll") for (int k = 0; k < 2; ++k) dst[m][k] = *(const PG8_LAS bf16x8*)(lds + PG8_SA(b, h) + aoff + m * 2048 + k * 1024); } while (0)
; #define PG8_LDB(dst, b, h) do { _Pragma("unroll") for (int n = 0; n < 2; ++n) _Pragma("unroll") for (int k = 0; k < 2; ++k) dst[n][k] = *(const PG8_LAS bf16x8*)(lds + PG8_SB(b, h) + boff + n * 2048 + k * 1024); } while (0)
; #define PG8_SCHED __builtin_amdgcn_sched_barrier(0)
;     ...
;         for (int t = 0; t < nt; t += 2) {
;             const bool last = (t == nt - 2);
;             const char* a1 = cA + (size_t)(t + 1) * kstep;
;             const char* a2 = last ? nA : cA + (size_t)(t + 2) * kstep; const char* b2 = last ? nB : cB + (size_t)(t + 2) * kstep;
;             const char* a3 = a2 + kstep; const char* b3 = b2 + kstep;
;             if (last && has_next) S.a_ready(nxt);
;             if constexpr (SP2) {
;             PG8_LDB(B0, 0, 0); PG8_LDB(B1, 0, 1); PG8_SCHED; PG8_LDA(At, 0, 0); PG8_STAGEA(PG8_SA(1, 1), a1 + hstep, voffA);
.Lsprio_6:
.LBB0_1054:
	v_add_u32_e32 v128, s59, v163
	ds_read_b128 v[166:169], v128
	ds_read_b128 v[170:173], v128 offset:1024
	ds_read_b128 v[176:179], v128 offset:2048
	ds_read_b128 v[180:183], v128 offset:3072
	v_add_u32_e32 v128, s70, v163
	ds_read_b128 v[184:187], v128
	ds_read_b128 v[188:191], v128 offset:1024
	ds_read_b128 v[192:195], v128 offset:2048
	ds_read_b128 v[196:199], v128 offset:3072
	s_add_u32 s44, s38, s42
	s_addc_u32 s45, s39, s43
	s_add_u32 s74, s36, s42
	s_addc_u32 s75, s37, s43
	s_cmp_eq_u32 s57, s73
	s_cselect_b32 s51, s13, s45
	s_cselect_b32 s50, s23, s44
	s_cselect_b32 s45, s25, s75
	s_cselect_b32 s44, s27, s74
	s_cmp_eq_u32 s99, 0x7777
	s_cbranch_scc1 .Lsp7_h
